# P2 three-way stagger of the HBM-bound sample-path item against the VALU-bound attention run (before / between halves / after)
# baseline (speedup 1.0000x reference)
.LBB0_289:
	s_or_b64 exec, exec, s[0:1]
	s_add_u32 s0, s24, 0x10000000
	s_addc_u32 s1, s25, 0
	v_writelane_b32 v247, s0, 21
	v_mov_b32_e32 v209, v222
	s_waitcnt lgkmcnt(0)
	v_writelane_b32 v247, s1, 22
	s_barrier
	v_writelane_b32 v247, s92, 23
	s_cmpk_lt_i32 s92, 0x100
	s_nop 0
	v_bfe_u32 v193, v209, 4, 2
	v_ashrrev_i32_e32 v112, 3, v209
	v_and_b32_e32 v189, 15, v209
	v_writelane_b32 v247, s93, 24
	s_mov_b32 s100, 0
	s_cbranch_scc0 .LBB0_394
	s_lshr_b32 s98, s92, 3
	s_mul_i32 s99, s98, 171
	s_lshr_b32 s99, s99, 9
	s_mul_i32 s99, s99, 3
	s_sub_i32 s98, s98, s99
	s_cmp_eq_u32 s98, 0
	s_cbranch_scc1 .Lstag_sample
	s_mov_b32 s100, 1
	s_cmp_eq_u32 s98, 1
	s_cbranch_scc1 .LBB0_394
	s_mov_b32 s100, 3
	s_branch .LBB0_394

.Lstag_attn0:
	s_cmp_eq_u32 s100, 4
	s_cbranch_scc0 .Lstag_attn
	s_mov_b32 s100, 5
.Lstag_attn:
	s_ashr_i32 s0, s26, 3
	v_readlane_b32 s2, v247, 18
	s_mul_i32 s0, s0, s2
	v_readlane_b32 s2, v247, 25
	s_and_b32 s1, s26, 7
	s_add_i32 s2, s0, s2
	s_ashr_i32 s29, s26, 31
	s_cmp_eq_u32 s1, 0
	v_readlane_b32 s88, v247, 23
	s_cselect_b32 s8, s2, s88
	s_mov_b32 s28, s26
	s_cmp_ge_u32 s100, 3
	s_cbranch_scc0 .Lstag_full
	s_lshl_b32 s8, s8, 1
	s_lshl_b32 s28, s28, 1
	s_cmp_eq_u32 s100, 5
	s_cbranch_scc0 .Lstag_full
	s_add_i32 s8, s8, 1
.Lstag_full:
	s_mul_hi_i32 s3, s8, 0xc00
	s_mul_i32 s2, s8, 0xc00
	s_or_b64 s[4:5], s[2:3], s[28:29]
	s_mov_b32 s0, 0
	s_mov_b32 s1, s5
	v_readlane_b32 s89, v247, 24
	s_cmp_lg_u64 s[0:1], 0
	s_cbranch_scc0 .LBB0_396
	s_ashr_i32 s0, s29, 31
	s_add_u32 s4, s28, s0
	s_mov_b32 s1, s0
	s_addc_u32 s5, s29, s0
	s_xor_b64 s[6:7], s[4:5], s[0:1]
	v_cvt_f32_u32_e32 v0, s6
	v_cvt_f32_u32_e32 v1, s7
	s_sub_u32 s9, 0, s6
	s_subb_u32 s12, 0, s7
	s_mov_b64 s[4:5], 0
	v_fmamk_f32 v0, v1, 0x4f800000, v0
	v_rcp_f32_e32 v0, v0
	s_nop 0
	v_mul_f32_e32 v0, 0x5f7ffffc, v0
	v_mul_f32_e32 v1, 0x2f800000, v0
	v_trunc_f32_e32 v1, v1
	v_fmamk_f32 v0, v1, 0xcf800000, v0
	v_cvt_u32_f32_e32 v1, v1
	v_cvt_u32_f32_e32 v0, v0
	v_readfirstlane_b32 s13, v1
	v_readfirstlane_b32 s10, v0
	s_mul_i32 s11, s9, s13
	s_mul_hi_u32 s15, s9, s10
	s_mul_i32 s14, s12, s10
	s_add_i32 s11, s15, s11
	s_add_i32 s11, s11, s14
	s_mul_i32 s16, s9, s10
	s_mul_i32 s15, s10, s11
	s_mul_hi_u32 s17, s10, s16
	s_mul_hi_u32 s14, s10, s11
	s_add_u32 s15, s17, s15
	s_addc_u32 s14, 0, s14
	s_mul_hi_u32 s18, s13, s16
	s_mul_i32 s16, s13, s16
	s_add_u32 s15, s15, s16
	s_mul_hi_u32 s17, s13, s11
	s_addc_u32 s14, s14, s18
	s_addc_u32 s15, s17, 0
	s_mul_i32 s11, s13, s11
	s_add_u32 s11, s14, s11
	s_addc_u32 s14, 0, s15
	s_add_u32 s15, s10, s11
	s_cselect_b64 s[10:11], -1, 0
	s_cmp_lg_u64 s[10:11], 0
	s_addc_u32 s13, s13, s14
	s_mul_i32 s10, s9, s13
	s_mul_hi_u32 s11, s9, s15
	s_add_i32 s10, s11, s10
	s_mul_i32 s12, s12, s15
	s_add_i32 s10, s10, s12
	s_mul_i32 s9, s9, s15
	s_mul_hi_u32 s12, s13, s9
	s_mul_i32 s14, s13, s9
	s_mul_i32 s17, s15, s10
	s_mul_hi_u32 s9, s15, s9
	s_mul_hi_u32 s16, s15, s10
	s_add_u32 s9, s9, s17
	s_addc_u32 s16, 0, s16
	s_add_u32 s9, s9, s14
	s_mul_hi_u32 s11, s13, s10
	s_addc_u32 s9, s16, s12
	s_addc_u32 s11, s11, 0
	s_mul_i32 s10, s13, s10
	s_add_u32 s9, s9, s10
	s_addc_u32 s12, 0, s11
	s_add_u32 s9, s15, s9
	s_cselect_b64 s[10:11], -1, 0
	s_cmp_lg_u64 s[10:11], 0
	s_addc_u32 s14, s13, s12
	s_ashr_i32 s10, s3, 31
	s_add_u32 s12, s2, s10
	s_mov_b32 s11, s10
	s_addc_u32 s13, s3, s10
	s_xor_b64 s[12:13], s[12:13], s[10:11]
	s_mul_i32 s15, s12, s14
	s_mul_hi_u32 s16, s12, s9
	s_mul_hi_u32 s3, s12, s14
	s_add_u32 s15, s16, s15
	s_addc_u32 s3, 0, s3
	s_mul_hi_u32 s17, s13, s9
	s_mul_i32 s9, s13, s9
	s_add_u32 s9, s15, s9
	s_mul_hi_u32 s16, s13, s14
	s_addc_u32 s3, s3, s17
	s_addc_u32 s9, s16, 0
	s_mul_i32 s14, s13, s14
	s_add_u32 s3, s3, s14
	s_addc_u32 s9, 0, s9
	s_mul_i32 s14, s6, s9
	s_mul_hi_u32 s15, s6, s3
	s_add_i32 s14, s15, s14
	s_mul_i32 s15, s7, s3
	s_add_i32 s18, s14, s15
	s_sub_i32 s16, s13, s18
	s_mul_i32 s14, s6, s3
	s_sub_u32 s12, s12, s14
	s_cselect_b64 s[14:15], -1, 0
	s_cmp_lg_u64 s[14:15], 0
	s_subb_u32 s19, s16, s7
	s_sub_u32 s30, s12, s6
	s_cselect_b64 s[16:17], -1, 0
	s_cmp_lg_u64 s[16:17], 0
	s_subb_u32 s16, s19, 0
	s_cmp_ge_u32 s16, s7
	s_cselect_b32 s17, -1, 0
	s_cmp_ge_u32 s30, s6
	s_cselect_b32 s19, -1, 0
	s_cmp_eq_u32 s16, s7
	s_cselect_b32 s16, s19, s17
	s_add_u32 s17, s3, 1
	s_addc_u32 s19, s9, 0
	s_add_u32 s30, s3, 2
	s_addc_u32 s31, s9, 0
	s_cmp_lg_u32 s16, 0
	s_cselect_b32 s16, s30, s17
	s_cselect_b32 s17, s31, s19
	s_cmp_lg_u64 s[14:15], 0
	s_subb_u32 s13, s13, s18
	s_cmp_ge_u32 s13, s7
	s_cselect_b32 s14, -1, 0
	s_cmp_ge_u32 s12, s6
	s_cselect_b32 s6, -1, 0
	s_cmp_eq_u32 s13, s7
	s_cselect_b32 s6, s6, s14
	s_cmp_lg_u32 s6, 0
	s_cselect_b32 s7, s17, s9
	s_cselect_b32 s6, s16, s3
	s_xor_b64 s[0:1], s[10:11], s[0:1]
	s_xor_b64 s[6:7], s[6:7], s[0:1]
	s_sub_u32 s0, s6, s0
	s_branch .LBB0_397

.LBB0_419:
	s_mov_b32 s28, s26
	s_cmp_eq_u32 s100, 3
	s_cbranch_scc0 .Lstag_c_cont
	s_mov_b32 s100, 4
	s_waitcnt vmcnt(0) lgkmcnt(0)
	s_branch .Lstag_sample

.LBB0_422:
	s_cmp_eq_u32 s100, 1
	s_cbranch_scc0 .Lstag_done
	s_mov_b32 s100, 2
	v_writelane_b32 v252, s4, 0
	v_writelane_b32 v252, s5, 1
	v_writelane_b32 v252, s6, 2
	v_writelane_b32 v252, s7, 3
	v_writelane_b32 v252, s10, 4
	v_writelane_b32 v252, s11, 5
	v_writelane_b32 v252, s14, 6
	v_writelane_b32 v252, s15, 7
	v_writelane_b32 v252, s16, 8
	v_writelane_b32 v252, s17, 9
	v_writelane_b32 v252, s18, 10
	v_writelane_b32 v252, s19, 11
	v_writelane_b32 v252, s28, 12
	v_writelane_b32 v252, s29, 13
	v_writelane_b32 v252, s30, 14
	v_writelane_b32 v252, s31, 15
	v_writelane_b32 v252, s34, 16
	v_writelane_b32 v252, s35, 17
	v_writelane_b32 v252, s41, 18
	v_writelane_b32 v252, s43, 19
	v_writelane_b32 v252, s54, 20
	v_writelane_b32 v252, s55, 21
	v_writelane_b32 v252, s56, 22
	v_writelane_b32 v252, s57, 23
	v_writelane_b32 v252, s58, 24
	v_writelane_b32 v252, s88, 25
	v_writelane_b32 v252, s89, 26
	v_writelane_b32 v252, s90, 27
	v_writelane_b32 v252, s91, 28
	v_writelane_b32 v252, s96, 29
	s_waitcnt vmcnt(0) lgkmcnt(0)
	s_branch .Lstag_sample
